# P6 epilogue loads hoisted (loads-only vmcnt) + L2 prefetch of cache_v lines before the sample-attention PV loop
# speedup vs baseline: 1.0062x; 1.0062x over previous
; #define LAS __attribute__((address_space(3)))
; __device__ __forceinline__ sbf16x8 pack_f8(f32x4 a, f32x4 b) { v4u w; w.x = cvtpk2(a.x, a.y); w.y = cvtpk2(a.z, a.w); w.z = cvtpk2(b.x, b.y); w.w = cvtpk2(b.z, b.w); return __builtin_bit_cast(sbf16x8, w); }
; __device__ __forceinline__ void sample_attn_item(const Args& A, LAS unsigned char* lds, int b, int h, int mm, int tid) {
;     ...
;     const int db = wave & 3, kh = wave >> 2;
;     sf32x16 o = sf32x16{};
;     for (int k2 = 33 * kh; k2 < 33 * kh + 33; ++k2) {
;         const LAS f32x4* pp = (const LAS f32x4*)(S + r32 * SP + k2 * 16 + hi * 8);
;         const sbf16x8 pa = pack_f8(pp[0], pp[1]);
;         sbf16x8 vf;
;         if (k2 < PAST / 16) { const float* vp = A.cache_v + ((size_t)(b * PAST + k2 * 16 + hi * 8) * 8 + h) * 128 + db * 32 + r32;
;             f32x4 v0, v1; v0.x = vp[0]; v0.y = vp[1024]; v0.z = vp[2048]; v0.w = vp[3072]; v1.x = vp[4096]; v1.y = vp[5120]; v1.z = vp[6144]; v1.w = vp[7168];
;             vf = pack_f8(v0, v1); }
.LBB0_877:
	s_bfe_u32 s10, s30, 0x20006
	s_ashr_i32 s22, s30, 8
	s_lshl_b32 s8, s27, 1
	s_add_u32 s8, s76, s8
	s_addc_u32 s9, s77, 0
	s_lshl_b32 s28, s10, 6
	s_waitcnt lgkmcnt(0)
	s_barrier
	s_add_u32 s8, s8, s28
	s_load_dwordx2 s[28:29], s[20:21], 0x18
	s_addc_u32 s9, s9, 0
	v_lshlrev_b32_e32 v24, 1, v44
	v_mov_b32_e32 v25, v49
	v_lshl_add_u64 v[26:27], s[8:9], 0, v[24:25]
	s_lshl_b32 s34, s34, 10
	s_lshl_b32 s8, s27, 2
	s_waitcnt lgkmcnt(0)
	s_add_u32 s8, s28, s8
	s_addc_u32 s9, s29, 0
	s_lshl_b32 s28, s10, 7
	s_add_u32 s8, s8, s28
	s_addc_u32 s9, s9, 0
	v_lshlrev_b32_e32 v0, 2, v44
	v_mov_b32_e32 v1, v49
	v_lshl_add_u64 v[28:29], s[8:9], 0, v[0:1]
	s_mul_i32 s8, s22, 0x210
	s_add_i32 s9, s8, s34
	s_add_i32 s31, s31, s8
	s_mul_i32 s8, s22, 0x840
	v_mov_b32_e32 v0, 0
	s_mul_i32 s23, s22, 33
	v_or_b32_e32 v25, s9, v46
	v_mbcnt_lo_u32_b32 v96, -1, 0
	v_mbcnt_hi_u32_b32 v96, -1, v96
	v_add_u32_e32 v96, s9, v96
	s_add_i32 s98, s34, 0x3ff
	v_mov_b32_e32 v99, 0
	v_min_u32_e32 v98, s98, v96
	v_lshl_add_u64 v[102:103], v[98:99], 12, v[28:29]
	global_load_dword v104, v[102:103], off
	v_add_u32_e32 v96, 64, v96
	v_min_u32_e32 v98, s98, v96
	v_lshl_add_u64 v[102:103], v[98:99], 12, v[28:29]
	global_load_dword v105, v[102:103], off
	v_add_u32_e32 v96, 64, v96
	v_min_u32_e32 v98, s98, v96
	v_lshl_add_u64 v[102:103], v[98:99], 12, v[28:29]
	global_load_dword v106, v[102:103], off
	v_add_u32_e32 v96, 64, v96
	v_min_u32_e32 v98, s98, v96
	v_lshl_add_u64 v[102:103], v[98:99], 12, v[28:29]
	global_load_dword v107, v[102:103], off
	v_add_u32_e32 v96, 64, v96
	v_min_u32_e32 v98, s98, v96
	v_lshl_add_u64 v[102:103], v[98:99], 12, v[28:29]
	global_load_dword v108, v[102:103], off
	v_add_u32_e32 v96, 64, v96
	v_min_u32_e32 v98, s98, v96
	v_lshl_add_u64 v[102:103], v[98:99], 12, v[28:29]
	global_load_dword v109, v[102:103], off
	v_add_u32_e32 v96, 64, v96
	v_min_u32_e32 v98, s98, v96
	v_lshl_add_u64 v[102:103], v[98:99], 12, v[28:29]
	global_load_dword v110, v[102:103], off
	v_add_u32_e32 v96, 64, v96
	v_min_u32_e32 v98, s98, v96
	v_lshl_add_u64 v[102:103], v[98:99], 12, v[28:29]
	global_load_dword v111, v[102:103], off
	v_add_u32_e32 v96, 64, v96
	v_min_u32_e32 v98, s98, v96
	v_lshl_add_u64 v[102:103], v[98:99], 12, v[28:29]
	global_load_dword v112, v[102:103], off
	v_add_u32_e32 v96, 64, v96
	v_add_u32_e32 v30, s31, v81
	v_add_u32_e32 v31, s8, v82
	s_mov_b32 s28, 0
	v_mov_b32_e32 v1, v0
	v_mov_b32_e32 v2, v0
	v_mov_b32_e32 v3, v0
	v_mov_b32_e32 v4, v0
	v_mov_b32_e32 v5, v0
	v_mov_b32_e32 v6, v0
	v_mov_b32_e32 v7, v0
	v_mov_b32_e32 v8, v0
	v_mov_b32_e32 v9, v0
	v_mov_b32_e32 v10, v0
	v_mov_b32_e32 v11, v0
	v_mov_b32_e32 v12, v0
	v_mov_b32_e32 v13, v0
	v_mov_b32_e32 v14, v0
	v_mov_b32_e32 v15, v0
	s_branch .LBB0_879

; __device__ __forceinline__ float bf_lo(unsigned w) { return __uint_as_float(w << 16); }
; __device__ __forceinline__ float bf_hi(unsigned w) { return __uint_as_float(w & 0xffff0000u); }
; __device__ __forceinline__ u32x4 pack8(f32x4 a, f32x4 b) { u32x4 w; w.x = cvt_pk_bf16(a[0], a[1]); w.y = cvt_pk_bf16(a[2], a[3]); w.z = cvt_pk_bf16(b[0], b[1]); w.w = cvt_pk_bf16(b[2], b[3]); return w; }
;     __device__ __forceinline__ void operator()(const f32x4 (&acc)[2][2][4][2], const Unit& u, int wr, int wc, int fr, int fq) const {
;         const int row0 = u.pm * BM + wr * 64 + fr, col0 = u.pn * BM + wc * 32 + 8 * fq;
;         const float* gp = gate + (size_t)(u.pm >> 5) * 6144 + col0;
;         f32x4 g[2][2];
; #pragma unroll
;         for (int bj = 0; bj < 2; ++bj) { g[bj][0] = *(const f32x4*)(gp + bj * HALF); g[bj][1] = *(const f32x4*)(gp + bj * HALF + 4); }
; #pragma unroll
;         for (int ai = 0; ai < 2; ++ai)
; #pragma unroll
;             for (int m = 0; m < 4; ++m) { const size_t ro = (size_t)(row0 + ai * HALF + m * 16) * 1024 + col0;
; #pragma unroll
;                 for (int bj = 0; bj < 2; ++bj) { const size_t o = ro + bj * HALF;
;                     if constexpr (!FINAL) { const f32x4 b0 = *(const f32x4*)(xin + o), b1 = *(const f32x4*)(xin + o + 4);
;                         *(u32x4*)(x1b + o) = pack8(b0 + g[bj][0] * acc[ai][bj][m][0], b1 + g[bj][1] * acc[ai][bj][m][1]); }
;                     else { const u32x4 w = *(const u32x4*)(x1b + o);
;                         const f32x4 b0 = {bf_lo(w.x), bf_hi(w.x), bf_lo(w.y), bf_hi(w.y)}, b1 = {bf_lo(w.z), bf_hi(w.z), bf_lo(w.w), bf_hi(w.w)};
;                         *(f32x4*)(out + o) = b0 + g[bj][0] * acc[ai][bj][m][0]; *(f32x4*)(out + o + 4) = b1 + g[bj][1] * acc[ai][bj][m][1]; } } }
.LBB0_1371:
	v_lshl_add_u32 v164, s58, 8, v167
	v_lshl_or_b32 v162, s59, 8, v169
	v_ashrrev_i32_e32 v165, 31, v164
	v_ashrrev_i32_e32 v163, 31, v162
	v_lshlrev_b64 v[120:121], 10, v[164:165]
	v_lshl_add_u64 v[160:161], v[120:121], 0, v[162:163]
	s_ashr_i32 s30, s58, 5
	v_lshlrev_b64 v[178:179], 1, v[160:161]
	s_mul_hi_i32 s31, s30, 0x6000
	s_mulk_i32 s30, 0x6000
	v_lshl_add_u64 v[182:183], s[6:7], 0, v[178:179]
	s_add_u32 s30, s33, s30
	s_addc_u32 s31, s40, s31
	v_lshl_add_u64 v[124:125], v[162:163], 2, s[30:31]
	global_load_dwordx4 v[132:135], v[124:125], off
	global_load_dwordx4 v[128:131], v[124:125], off offset:16
	global_load_dwordx4 v[120:123], v[124:125], off offset:528
	s_nop 0
	global_load_dwordx4 v[124:127], v[124:125], off offset:512
	v_lshl_add_u64 v[160:161], v[160:161], 2, s[8:9]
	s_and_b64 vcc, exec, s[0:1]
	s_mov_b64 s[0:1], -1
	s_mov_b32 s98, 0x8000
	s_mov_b32 s99, 0
	s_mov_b32 s100, 0x10000
	s_mov_b32 s101, 0
	global_load_dwordx4 v[184:187], v[182:183], off
	global_load_dwordx4 v[188:191], v[182:183], off offset:256
	v_lshl_add_u64 v[182:183], v[182:183], 0, s[98:99]
	global_load_dwordx4 v[192:195], v[182:183], off
	global_load_dwordx4 v[196:199], v[182:183], off offset:256
	v_lshl_add_u64 v[182:183], v[182:183], 0, s[98:99]
	global_load_dwordx4 v[200:203], v[182:183], off
	global_load_dwordx4 v[204:207], v[182:183], off offset:256
	v_lshl_add_u64 v[182:183], v[182:183], 0, s[98:99]
	global_load_dwordx4 v[208:211], v[182:183], off
	global_load_dwordx4 v[212:215], v[182:183], off offset:256
	v_lshl_add_u64 v[182:183], v[182:183], 0, s[98:99]
	v_lshl_add_u64 v[182:183], v[182:183], 0, s[98:99]
	v_lshl_add_u64 v[182:183], v[182:183], 0, s[98:99]
	v_lshl_add_u64 v[182:183], v[182:183], 0, s[98:99]
	v_lshl_add_u64 v[182:183], v[182:183], 0, s[98:99]
	global_load_dwordx4 v[216:219], v[182:183], off
	global_load_dwordx4 v[220:223], v[182:183], off offset:256
	v_lshl_add_u64 v[182:183], v[182:183], 0, s[98:99]
	global_load_dwordx4 v[224:227], v[182:183], off
	global_load_dwordx4 v[232:235], v[182:183], off offset:256
	v_lshl_add_u64 v[182:183], v[182:183], 0, s[98:99]
	global_load_dwordx4 v[236:239], v[182:183], off
	global_load_dwordx4 v[240:243], v[182:183], off offset:256
	v_lshl_add_u64 v[182:183], v[182:183], 0, s[98:99]
	global_load_dwordx4 v[244:247], v[182:183], off
	global_load_dwordx4 v[252:255], v[182:183], off offset:256
	s_waitcnt vmcnt(15)
	v_lshlrev_b32_e32 v174, 16, v184
	v_and_b32_e32 v175, 0xffff0000, v184
	v_lshlrev_b32_e32 v176, 16, v185
	v_and_b32_e32 v177, 0xffff0000, v185
	v_lshlrev_b32_e32 v178, 16, v186
	v_and_b32_e32 v179, 0xffff0000, v186
	v_lshlrev_b32_e32 v180, 16, v187
	v_and_b32_e32 v181, 0xffff0000, v187
	v_pk_fma_f32 v[140:141], v[140:141], v[132:133], v[174:175]
	v_pk_fma_f32 v[142:143], v[142:143], v[134:135], v[176:177]
	v_pk_fma_f32 v[136:137], v[136:137], v[128:129], v[178:179]
	v_pk_fma_f32 v[138:139], v[138:139], v[130:131], v[180:181]
	global_store_dwordx4 v[160:161], v[140:143], off
	global_store_dwordx4 v[160:161], v[136:139], off offset:16
	s_waitcnt vmcnt(14)
	v_lshlrev_b32_e32 v174, 16, v188
	v_and_b32_e32 v175, 0xffff0000, v188
	v_lshlrev_b32_e32 v176, 16, v189
	v_and_b32_e32 v177, 0xffff0000, v189
	v_lshlrev_b32_e32 v178, 16, v190
	v_and_b32_e32 v179, 0xffff0000, v190
	v_lshlrev_b32_e32 v180, 16, v191
	v_and_b32_e32 v181, 0xffff0000, v191
	v_pk_fma_f32 v[116:117], v[116:117], v[124:125], v[174:175]
	v_pk_fma_f32 v[118:119], v[118:119], v[126:127], v[176:177]
	v_pk_fma_f32 v[112:113], v[112:113], v[120:121], v[178:179]
	v_pk_fma_f32 v[114:115], v[114:115], v[122:123], v[180:181]
	global_store_dwordx4 v[160:161], v[116:119], off offset:512
	global_store_dwordx4 v[160:161], v[112:115], off offset:528
	v_lshl_add_u64 v[160:161], v[160:161], 0, s[100:101]
	s_waitcnt vmcnt(13)
	v_lshlrev_b32_e32 v174, 16, v192
	v_and_b32_e32 v175, 0xffff0000, v192
	v_lshlrev_b32_e32 v176, 16, v193
	v_and_b32_e32 v177, 0xffff0000, v193
	v_lshlrev_b32_e32 v178, 16, v194
	v_and_b32_e32 v179, 0xffff0000, v194
	v_lshlrev_b32_e32 v180, 16, v195
	v_and_b32_e32 v181, 0xffff0000, v195
	v_pk_fma_f32 v[108:109], v[108:109], v[132:133], v[174:175]
	v_pk_fma_f32 v[110:111], v[110:111], v[134:135], v[176:177]
	v_pk_fma_f32 v[104:105], v[104:105], v[128:129], v[178:179]
	v_pk_fma_f32 v[106:107], v[106:107], v[130:131], v[180:181]
	global_store_dwordx4 v[160:161], v[108:111], off
	global_store_dwordx4 v[160:161], v[104:107], off offset:16
	s_waitcnt vmcnt(12)
	v_lshlrev_b32_e32 v174, 16, v196
	v_and_b32_e32 v175, 0xffff0000, v196
	v_lshlrev_b32_e32 v176, 16, v197
	v_and_b32_e32 v177, 0xffff0000, v197
	v_lshlrev_b32_e32 v178, 16, v198
	v_and_b32_e32 v179, 0xffff0000, v198
	v_lshlrev_b32_e32 v180, 16, v199
	v_and_b32_e32 v181, 0xffff0000, v199
	v_pk_fma_f32 v[100:101], v[100:101], v[124:125], v[174:175]
	v_pk_fma_f32 v[102:103], v[102:103], v[126:127], v[176:177]
	v_pk_fma_f32 v[96:97], v[96:97], v[120:121], v[178:179]
	v_pk_fma_f32 v[98:99], v[98:99], v[122:123], v[180:181]
	global_store_dwordx4 v[160:161], v[100:103], off offset:512
	global_store_dwordx4 v[160:161], v[96:99], off offset:528
	v_lshl_add_u64 v[160:161], v[160:161], 0, s[100:101]
	s_waitcnt vmcnt(11)
	v_lshlrev_b32_e32 v174, 16, v200
	v_and_b32_e32 v175, 0xffff0000, v200
	v_lshlrev_b32_e32 v176, 16, v201
	v_and_b32_e32 v177, 0xffff0000, v201
	v_lshlrev_b32_e32 v178, 16, v202
	v_and_b32_e32 v179, 0xffff0000, v202
	v_lshlrev_b32_e32 v180, 16, v203
	v_and_b32_e32 v181, 0xffff0000, v203
	v_pk_fma_f32 v[92:93], v[92:93], v[132:133], v[174:175]
	v_pk_fma_f32 v[94:95], v[94:95], v[134:135], v[176:177]
	v_pk_fma_f32 v[88:89], v[88:89], v[128:129], v[178:179]
	v_pk_fma_f32 v[90:91], v[90:91], v[130:131], v[180:181]
	global_store_dwordx4 v[160:161], v[92:95], off
	global_store_dwordx4 v[160:161], v[88:91], off offset:16
	s_waitcnt vmcnt(10)
; __device__ __forceinline__ float bf_lo(unsigned w) { return __uint_as_float(w << 16); }
; __device__ __forceinline__ float bf_hi(unsigned w) { return __uint_as_float(w & 0xffff0000u); }
; __device__ __forceinline__ u32x4 pack8(f32x4 a, f32x4 b) { u32x4 w; w.x = cvt_pk_bf16(a[0], a[1]); w.y = cvt_pk_bf16(a[2], a[3]); w.z = cvt_pk_bf16(b[0], b[1]); w.w = cvt_pk_bf16(b[2], b[3]); return w; }
;     __device__ __forceinline__ void operator()(const f32x4 (&acc)[2][2][4][2], const Unit& u, int wr, int wc, int fr, int fq) const {
;     ...
;         for (int ai = 0; ai < 2; ++ai)
; #pragma unroll
;             for (int m = 0; m < 4; ++m) { const size_t ro = (size_t)(row0 + ai * HALF + m * 16) * 1024 + col0;
; #pragma unroll
;                 for (int bj = 0; bj < 2; ++bj) { const size_t o = ro + bj * HALF;
;                     if constexpr (!FINAL) { const f32x4 b0 = *(const f32x4*)(xin + o), b1 = *(const f32x4*)(xin + o + 4);
;                         *(u32x4*)(x1b + o) = pack8(b0 + g[bj][0] * acc[ai][bj][m][0], b1 + g[bj][1] * acc[ai][bj][m][1]); }
;                     else { const u32x4 w = *(const u32x4*)(x1b + o);
;                         const f32x4 b0 = {bf_lo(w.x), bf_hi(w.x), bf_lo(w.y), bf_hi(w.y)}, b1 = {bf_lo(w.z), bf_hi(w.z), bf_lo(w.w), bf_hi(w.w)};
;                         *(f32x4*)(out + o) = b0 + g[bj][0] * acc[ai][bj][m][0]; *(f32x4*)(out + o + 4) = b1 + g[bj][1] * acc[ai][bj][m][1]; } } }
	v_lshlrev_b32_e32 v174, 16, v204
	v_and_b32_e32 v175, 0xffff0000, v204
	v_lshlrev_b32_e32 v176, 16, v205
	v_and_b32_e32 v177, 0xffff0000, v205
	v_lshlrev_b32_e32 v178, 16, v206
	v_and_b32_e32 v179, 0xffff0000, v206
	v_lshlrev_b32_e32 v180, 16, v207
	v_and_b32_e32 v181, 0xffff0000, v207
	v_pk_fma_f32 v[84:85], v[84:85], v[124:125], v[174:175]
	v_pk_fma_f32 v[86:87], v[86:87], v[126:127], v[176:177]
	v_pk_fma_f32 v[80:81], v[80:81], v[120:121], v[178:179]
	v_pk_fma_f32 v[82:83], v[82:83], v[122:123], v[180:181]
	global_store_dwordx4 v[160:161], v[84:87], off offset:512
	global_store_dwordx4 v[160:161], v[80:83], off offset:528
	v_lshl_add_u64 v[160:161], v[160:161], 0, s[100:101]
	s_waitcnt vmcnt(9)
	v_lshlrev_b32_e32 v174, 16, v208
	v_and_b32_e32 v175, 0xffff0000, v208
	v_lshlrev_b32_e32 v176, 16, v209
	v_and_b32_e32 v177, 0xffff0000, v209
	v_lshlrev_b32_e32 v178, 16, v210
	v_and_b32_e32 v179, 0xffff0000, v210
	v_lshlrev_b32_e32 v180, 16, v211
	v_and_b32_e32 v181, 0xffff0000, v211
	v_pk_fma_f32 v[76:77], v[76:77], v[132:133], v[174:175]
	v_pk_fma_f32 v[78:79], v[78:79], v[134:135], v[176:177]
	v_pk_fma_f32 v[72:73], v[72:73], v[128:129], v[178:179]
	v_pk_fma_f32 v[74:75], v[74:75], v[130:131], v[180:181]
	global_store_dwordx4 v[160:161], v[76:79], off
	global_store_dwordx4 v[160:161], v[72:75], off offset:16
	s_waitcnt vmcnt(8)
	v_lshlrev_b32_e32 v174, 16, v212
	v_and_b32_e32 v175, 0xffff0000, v212
	v_lshlrev_b32_e32 v176, 16, v213
	v_and_b32_e32 v177, 0xffff0000, v213
	v_lshlrev_b32_e32 v178, 16, v214
	v_and_b32_e32 v179, 0xffff0000, v214
	v_lshlrev_b32_e32 v180, 16, v215
	v_and_b32_e32 v181, 0xffff0000, v215
	v_pk_fma_f32 v[68:69], v[68:69], v[124:125], v[174:175]
	v_pk_fma_f32 v[70:71], v[70:71], v[126:127], v[176:177]
	v_pk_fma_f32 v[64:65], v[64:65], v[120:121], v[178:179]
	v_pk_fma_f32 v[66:67], v[66:67], v[122:123], v[180:181]
	global_store_dwordx4 v[160:161], v[68:71], off offset:512
	global_store_dwordx4 v[160:161], v[64:67], off offset:528
	v_lshl_add_u64 v[160:161], v[160:161], 0, s[100:101]
	v_lshl_add_u64 v[160:161], v[160:161], 0, s[100:101]
	v_lshl_add_u64 v[160:161], v[160:161], 0, s[100:101]
	v_lshl_add_u64 v[160:161], v[160:161], 0, s[100:101]
	v_lshl_add_u64 v[160:161], v[160:161], 0, s[100:101]
	s_waitcnt vmcnt(7)
	v_lshlrev_b32_e32 v174, 16, v216
	v_and_b32_e32 v175, 0xffff0000, v216
	v_lshlrev_b32_e32 v176, 16, v217
	v_and_b32_e32 v177, 0xffff0000, v217
	v_lshlrev_b32_e32 v178, 16, v218
	v_and_b32_e32 v179, 0xffff0000, v218
	v_lshlrev_b32_e32 v180, 16, v219
	v_and_b32_e32 v181, 0xffff0000, v219
	v_pk_fma_f32 v[60:61], v[60:61], v[132:133], v[174:175]
	v_pk_fma_f32 v[62:63], v[62:63], v[134:135], v[176:177]
	v_pk_fma_f32 v[56:57], v[56:57], v[128:129], v[178:179]
	v_pk_fma_f32 v[58:59], v[58:59], v[130:131], v[180:181]
	global_store_dwordx4 v[160:161], v[60:63], off
	global_store_dwordx4 v[160:161], v[56:59], off offset:16
	s_waitcnt vmcnt(6)
	v_lshlrev_b32_e32 v174, 16, v220
	v_and_b32_e32 v175, 0xffff0000, v220
	v_lshlrev_b32_e32 v176, 16, v221
	v_and_b32_e32 v177, 0xffff0000, v221
	v_lshlrev_b32_e32 v178, 16, v222
	v_and_b32_e32 v179, 0xffff0000, v222
	v_lshlrev_b32_e32 v180, 16, v223
	v_and_b32_e32 v181, 0xffff0000, v223
	v_pk_fma_f32 v[52:53], v[52:53], v[124:125], v[174:175]
	v_pk_fma_f32 v[54:55], v[54:55], v[126:127], v[176:177]
	v_pk_fma_f32 v[48:49], v[48:49], v[120:121], v[178:179]
	v_pk_fma_f32 v[50:51], v[50:51], v[122:123], v[180:181]
	global_store_dwordx4 v[160:161], v[52:55], off offset:512
	global_store_dwordx4 v[160:161], v[48:51], off offset:528
	v_lshl_add_u64 v[160:161], v[160:161], 0, s[100:101]
	s_waitcnt vmcnt(5)
; __device__ __forceinline__ float bf_lo(unsigned w) { return __uint_as_float(w << 16); }
; __device__ __forceinline__ float bf_hi(unsigned w) { return __uint_as_float(w & 0xffff0000u); }
; __device__ __forceinline__ u32x4 pack8(f32x4 a, f32x4 b) { u32x4 w; w.x = cvt_pk_bf16(a[0], a[1]); w.y = cvt_pk_bf16(a[2], a[3]); w.z = cvt_pk_bf16(b[0], b[1]); w.w = cvt_pk_bf16(b[2], b[3]); return w; }
;     __device__ __forceinline__ void operator()(const f32x4 (&acc)[2][2][4][2], const Unit& u, int wr, int wc, int fr, int fq) const {
;     ...
;         for (int ai = 0; ai < 2; ++ai)
; #pragma unroll
;             for (int m = 0; m < 4; ++m) { const size_t ro = (size_t)(row0 + ai * HALF + m * 16) * 1024 + col0;
; #pragma unroll
;                 for (int bj = 0; bj < 2; ++bj) { const size_t o = ro + bj * HALF;
;                     if constexpr (!FINAL) { const f32x4 b0 = *(const f32x4*)(xin + o), b1 = *(const f32x4*)(xin + o + 4);
;                         *(u32x4*)(x1b + o) = pack8(b0 + g[bj][0] * acc[ai][bj][m][0], b1 + g[bj][1] * acc[ai][bj][m][1]); }
;                     else { const u32x4 w = *(const u32x4*)(x1b + o);
;                         const f32x4 b0 = {bf_lo(w.x), bf_hi(w.x), bf_lo(w.y), bf_hi(w.y)}, b1 = {bf_lo(w.z), bf_hi(w.z), bf_lo(w.w), bf_hi(w.w)};
;                         *(f32x4*)(out + o) = b0 + g[bj][0] * acc[ai][bj][m][0]; *(f32x4*)(out + o + 4) = b1 + g[bj][1] * acc[ai][bj][m][1]; } } }
	v_lshlrev_b32_e32 v174, 16, v224
	v_and_b32_e32 v175, 0xffff0000, v224
	v_lshlrev_b32_e32 v176, 16, v225
	v_and_b32_e32 v177, 0xffff0000, v225
	v_lshlrev_b32_e32 v178, 16, v226
	v_and_b32_e32 v179, 0xffff0000, v226
	v_lshlrev_b32_e32 v180, 16, v227
	v_and_b32_e32 v181, 0xffff0000, v227
	v_pk_fma_f32 v[44:45], v[44:45], v[132:133], v[174:175]
	v_pk_fma_f32 v[46:47], v[46:47], v[134:135], v[176:177]
	v_pk_fma_f32 v[40:41], v[40:41], v[128:129], v[178:179]
	v_pk_fma_f32 v[42:43], v[42:43], v[130:131], v[180:181]
	global_store_dwordx4 v[160:161], v[44:47], off
	global_store_dwordx4 v[160:161], v[40:43], off offset:16
	s_waitcnt vmcnt(4)
	v_lshlrev_b32_e32 v174, 16, v232
	v_and_b32_e32 v175, 0xffff0000, v232
	v_lshlrev_b32_e32 v176, 16, v233
	v_and_b32_e32 v177, 0xffff0000, v233
	v_lshlrev_b32_e32 v178, 16, v234
	v_and_b32_e32 v179, 0xffff0000, v234
	v_lshlrev_b32_e32 v180, 16, v235
	v_and_b32_e32 v181, 0xffff0000, v235
	v_pk_fma_f32 v[36:37], v[36:37], v[124:125], v[174:175]
	v_pk_fma_f32 v[38:39], v[38:39], v[126:127], v[176:177]
	v_pk_fma_f32 v[32:33], v[32:33], v[120:121], v[178:179]
	v_pk_fma_f32 v[34:35], v[34:35], v[122:123], v[180:181]
	global_store_dwordx4 v[160:161], v[36:39], off offset:512
	global_store_dwordx4 v[160:161], v[32:35], off offset:528
	v_lshl_add_u64 v[160:161], v[160:161], 0, s[100:101]
	s_waitcnt vmcnt(3)
	v_lshlrev_b32_e32 v174, 16, v236
	v_and_b32_e32 v175, 0xffff0000, v236
	v_lshlrev_b32_e32 v176, 16, v237
	v_and_b32_e32 v177, 0xffff0000, v237
	v_lshlrev_b32_e32 v178, 16, v238
	v_and_b32_e32 v179, 0xffff0000, v238
	v_lshlrev_b32_e32 v180, 16, v239
	v_and_b32_e32 v181, 0xffff0000, v239
	v_pk_fma_f32 v[28:29], v[28:29], v[132:133], v[174:175]
	v_pk_fma_f32 v[30:31], v[30:31], v[134:135], v[176:177]
	v_pk_fma_f32 v[24:25], v[24:25], v[128:129], v[178:179]
	v_pk_fma_f32 v[26:27], v[26:27], v[130:131], v[180:181]
	global_store_dwordx4 v[160:161], v[28:31], off
	global_store_dwordx4 v[160:161], v[24:27], off offset:16
	s_waitcnt vmcnt(2)
	v_lshlrev_b32_e32 v174, 16, v240
	v_and_b32_e32 v175, 0xffff0000, v240
	v_lshlrev_b32_e32 v176, 16, v241
	v_and_b32_e32 v177, 0xffff0000, v241
	v_lshlrev_b32_e32 v178, 16, v242
	v_and_b32_e32 v179, 0xffff0000, v242
	v_lshlrev_b32_e32 v180, 16, v243
	v_and_b32_e32 v181, 0xffff0000, v243
	v_pk_fma_f32 v[20:21], v[20:21], v[124:125], v[174:175]
	v_pk_fma_f32 v[22:23], v[22:23], v[126:127], v[176:177]
	v_pk_fma_f32 v[16:17], v[16:17], v[120:121], v[178:179]
	v_pk_fma_f32 v[18:19], v[18:19], v[122:123], v[180:181]
	global_store_dwordx4 v[160:161], v[20:23], off offset:512
	global_store_dwordx4 v[160:161], v[16:19], off offset:528
	v_lshl_add_u64 v[160:161], v[160:161], 0, s[100:101]
	s_waitcnt vmcnt(1)
	v_lshlrev_b32_e32 v174, 16, v244
	v_and_b32_e32 v175, 0xffff0000, v244
	v_lshlrev_b32_e32 v176, 16, v245
	v_and_b32_e32 v177, 0xffff0000, v245
	v_lshlrev_b32_e32 v178, 16, v246
	v_and_b32_e32 v179, 0xffff0000, v246
	v_lshlrev_b32_e32 v180, 16, v247
	v_and_b32_e32 v181, 0xffff0000, v247
	v_pk_fma_f32 v[12:13], v[12:13], v[132:133], v[174:175]
	v_pk_fma_f32 v[14:15], v[14:15], v[134:135], v[176:177]
	v_pk_fma_f32 v[8:9], v[8:9], v[128:129], v[178:179]
	v_pk_fma_f32 v[10:11], v[10:11], v[130:131], v[180:181]
	global_store_dwordx4 v[160:161], v[12:15], off
	global_store_dwordx4 v[160:161], v[8:11], off offset:16
	s_waitcnt vmcnt(0)
	v_lshlrev_b32_e32 v174, 16, v252
	v_and_b32_e32 v175, 0xffff0000, v252
	v_lshlrev_b32_e32 v176, 16, v253
	v_and_b32_e32 v177, 0xffff0000, v253
	v_lshlrev_b32_e32 v178, 16, v254
	v_and_b32_e32 v179, 0xffff0000, v254
	v_lshlrev_b32_e32 v180, 16, v255
	v_and_b32_e32 v181, 0xffff0000, v255
	v_pk_fma_f32 v[4:5], v[4:5], v[124:125], v[174:175]
	v_pk_fma_f32 v[6:7], v[6:7], v[126:127], v[176:177]
	v_pk_fma_f32 v[0:1], v[0:1], v[120:121], v[178:179]
	v_pk_fma_f32 v[2:3], v[2:3], v[122:123], v[180:181]
	global_store_dwordx4 v[160:161], v[4:7], off offset:512
	global_store_dwordx4 v[160:161], v[0:3], off offset:528
	s_cbranch_vccnz .LBB0_1356
	s_andn2_b64 vcc, exec, s[12:13]
	s_cbranch_vccnz .LBB0_1355
	s_barrier
	s_branch .LBB0_1355
